# P4 epilogue: hand-written rotated paths for the product (mode 1) and sigmoid-gate (mode 3) column tiles; other tiles unchanged
# speedup vs baseline: 1.0041x; 1.0041x over previous
; #define PG8_LAS __attribute__((address_space(3)))
;     __device__ __forceinline__ void operator()(const f32x4 (&acc)[2][2][4][2], const Unit& u, int wr, int wc, int fr, int fq) const {
;     ...
;         const PG8_LAS float* bp = (const PG8_LAS float*)(scr + 16384) + tcol;
;         const f32x4 ba0 = *(const PG8_LAS f32x4*)bp, ba1 = *(const PG8_LAS f32x4*)(bp + 4), bb0 = *(const PG8_LAS f32x4*)(bp + HALF), bb1 = *(const PG8_LAS f32x4*)(bp + HALF + 4);
;         int mode, pitch, c0, c1; bf16_t* dst;
;         if (pn < 4)       { mode = 0; dst = BG;  pitch = DM;  c0 = pn * BM + wc * 64 + fq * 8; c1 = c0 + 32; }
;         else if (pn < 12) { mode = 1; dst = CU;  pitch = DM;  c0 = (pn - 4) * HALF + tcol; c1 = c0; }
;         else if (pn < 16) { mode = 2; dst = Q;   pitch = DM;  c0 = (4 * (pn - 12) + wc) * 64 + fq * 8; c1 = c0 + 32; }
;         else if (pn < 17) { mode = 2; dst = K;   pitch = 256; c0 = wc * 64 + fq * 8; c1 = c0 + 32; }
;         else if (pn < 18) { mode = 0; dst = V;   pitch = 256; c0 = wc * 64 + fq * 8; c1 = c0 + 32; }
;         else              { mode = 3; dst = SZC; pitch = DM;  c0 = (pn - 18) * HALF + tcol; c1 = c0; }
.LBB0_444:
	v_mov_b32_e32 v175, v1
	v_mov_b32_e32 v147, v201
	s_cmp_gt_i32 s6, 3
	v_lshlrev_b32_e32 v164, 3, v147
	v_add_u32_e32 v146, s80, v164
	v_lshl_add_u32 v42, v146, 2, 0
	v_add_u32_e32 v42, 0x24000, v42
	ds_read_b128 v[54:57], v42
	ds_read_b128 v[50:53], v42 offset:16
	ds_read_b128 v[46:49], v42 offset:512
	ds_read_b128 v[42:45], v42 offset:528
	s_cmp_gt_u32 s6, 17
	s_cbranch_scc1 .Lp4e_m3
	s_add_i32 s5, s6, -4
	s_cmp_lt_u32 s5, 8
	s_cbranch_scc1 .Lp4e_m1
	s_cmp_gt_i32 s6, 3
	s_mov_b64 s[60:61], -1
	s_cbranch_scc0 .LBB0_460
	s_cmp_gt_u32 s6, 11
	s_mov_b64 s[56:57], -1
	s_cbranch_scc0 .LBB0_458
	s_cmp_gt_u32 s6, 15
	s_cbranch_scc0 .LBB0_455
	s_cmp_lg_u32 s6, 16
	s_mov_b64 s[54:55], -1
	s_cbranch_scc0 .LBB0_453
	s_mov_b64 s[58:59], -1
	s_cmp_gt_u32 s6, 17
	s_mov_b64 s[10:11], -1
	s_cbranch_scc0 .LBB0_450
	s_lshl_b32 s5, s6, 7
	s_addk_i32 s5, 0xf700
	v_add_u32_e32 v204, s5, v146
	s_mov_b64 s[10:11], 0

; __device__ __forceinline__ u32x4 pack8(const f32x4 a, const f32x4 b) { u32x4 w; w.x = cvt_pk_bf16(a[0], a[1]); w.y = cvt_pk_bf16(a[2], a[3]); w.z = cvt_pk_bf16(b[0], b[1]); w.w = cvt_pk_bf16(b[2], b[3]); return w; }
; #define EPI_ROWS _Pragma("unroll") for (int ai = 0; ai < 2; ++ai) _Pragma("unroll") for (int m = 0; m < 4; ++m)
;     __device__ __forceinline__ void operator()(const f32x4 (&acc)[2][2][4][2], const Unit& u, int wr, int wc, int fr, int fq) const {
;     ...
;         EPI_ROWS { rsv[ai][m] = rstd_lds(scr, EPI_LROW); asm volatile("" : "+v"(rsv[ai][m]) :: "memory"); }
;     ...
; #pragma unroll
;         for (int r = 0; r < 8; ++r) { const int ai = r >> 2, m = r & 3; const int row = EPI_ROW; const float rs = rsv[ai][m];
;             f32x4 a0 = acc[ai][0][m][0] * rs + ba0, a1 = acc[ai][0][m][1] * rs + ba1, b0 = acc[ai][1][m][0] * rs + bb0, b1 = acc[ai][1][m][1] * rs + bb1;
;             bf16_t* rp = dst + (size_t)row * pitch;
;             if (mode == 1) { *(u32x4*)(rp + c0) = pack8(a0 * b0, a1 * b1); }
.LBB0_574:
	s_nop 0
	v_ashrrev_i32_e32 v18, 31, v36
	v_mul_lo_u32 v20, s53, v36
	v_mul_lo_u32 v21, s52, v18
	v_mad_u64_u32 v[18:19], s[4:5], s52, v36, 0
	v_add3_u32 v19, v19, v21, v20
	v_pk_mul_f32 v[6:7], v[14:15], v[6:7]
	v_pk_mul_f32 v[12:13], v[12:13], v[4:5]
	v_pk_mul_f32 v[4:5], v[10:11], v[2:3]
	v_cvt_pk_bf16_f32 v2, v6, v7
	v_lshl_add_u64 v[6:7], v[18:19], 1, v[148:149]
	v_pk_mul_f32 v[8:9], v[16:17], v[8:9]
	s_nop 0
	v_cvt_pk_bf16_f32 v3, v8, v9
	v_cvt_pk_bf16_f32 v4, v4, v5
	v_cvt_pk_bf16_f32 v5, v12, v13
	global_store_dwordx4 v[6:7], v[2:5], off
	s_andn2_b64 vcc, exec, s[2:3]
	s_mov_b64 s[2:3], -1
	s_cbranch_vccnz .LBB0_434
	s_branch .LBB0_575
.Lp4e_m1:
	v_mov_b32_e32 v202, 0x358637bd
	v_lshlrev_b32_e32 v146, 6, v1
	v_lshl_add_u32 v147, v201, 10, v146
	v_add_u32_e32 v147, s89, v147
	ds_read_b128 v[148:151], v147
	ds_read_b128 v[152:155], v147 offset:16
	ds_read_b128 v[156:159], v147 offset:32
	ds_read_b128 v[160:163], v147 offset:48
	ds_read_b128 v[230:233], v147 offset:8192
	ds_read_b128 v[234:237], v147 offset:8208
	ds_read_b128 v[238:241], v147 offset:8224
	ds_read_b128 v[242:245], v147 offset:8240
	s_lshl_b32 s5, s4, 8
	s_add_i32 s5, s5, s79
	s_lshl_b32 s5, s5, 11
	s_add_i32 s7, s6, -4
	s_lshl_b32 s7, s7, 7
	s_add_i32 s7, s7, s80
	s_lshl_b32 s7, s7, 1
	s_add_u32 s5, s5, s7
	s_add_u32 s28, s24, s5
	s_addc_u32 s29, s25, 0
	v_lshlrev_b32_e32 v176, 11, v1
	v_lshl_add_u32 v176, v201, 4, v176
	s_lshr_b32 s9, s79, 4
	s_lshr_b32 s8, s80, 5
	s_add_u32 s9, s9, s8
	s_mov_b32 s8, 8
	s_waitcnt lgkmcnt(4)
	v_pk_add_f32 v[150:151], v[150:151], v[154:155]
	v_pk_add_f32 v[148:149], v[148:149], v[152:153]
	v_pk_add_f32 v[152:153], v[158:159], v[162:163]
	v_pk_add_f32 v[154:155], v[156:157], v[160:161]
	v_pk_add_f32 v[150:151], v[150:151], v[152:153]
	v_pk_add_f32 v[148:149], v[148:149], v[154:155]
	v_add_f32_e32 v148, v148, v149
	v_add_f32_e32 v150, v150, v151
	v_add_f32_e32 v148, v148, v150
	v_fmamk_f32 v148, v148, 0x3a800000, v202
	v_rsq_f32_e32 v148, v148
	s_waitcnt lgkmcnt(0)
	v_pk_add_f32 v[232:233], v[232:233], v[236:237]
	v_pk_add_f32 v[230:231], v[230:231], v[234:235]
	v_pk_add_f32 v[234:235], v[240:241], v[244:245]
	v_pk_add_f32 v[236:237], v[238:239], v[242:243]
	v_pk_add_f32 v[232:233], v[232:233], v[234:235]
	v_pk_add_f32 v[230:231], v[230:231], v[236:237]
	v_add_f32_e32 v230, v230, v231
	v_add_f32_e32 v232, v232, v233
	v_add_f32_e32 v230, v230, v232
	v_fmamk_f32 v230, v230, 0x3a800000, v202
	v_rsq_f32_e32 v230, v230
	v_lshlrev_b32_e32 v149, 2, v1
	v_add_u32_e32 v150, 0x40, v149
	v_add_u32_e32 v151, 0x80, v149
	v_add_u32_e32 v153, 0xc0, v149
	ds_bpermute_b32 v164, v149, v148
	ds_bpermute_b32 v166, v150, v148
	ds_bpermute_b32 v168, v151, v148
	ds_bpermute_b32 v170, v153, v148
	ds_bpermute_b32 v156, v149, v230
	ds_bpermute_b32 v158, v150, v230
	ds_bpermute_b32 v160, v151, v230
	ds_bpermute_b32 v162, v153, v230
	s_waitcnt lgkmcnt(0)
	s_cmp_eq_u32 s9, 1
	s_cbranch_scc1 .Lp4e_m1_rg1
	s_cmp_eq_u32 s9, 2
	s_cbranch_scc1 .Lp4e_m1_rg2
	s_cmp_eq_u32 s9, 3
	s_cbranch_scc1 .Lp4e_m1_rg3
	s_cmp_eq_u32 s9, 4
	s_cbranch_scc1 .Lp4e_m1_rg4
	s_cmp_eq_u32 s9, 5
	s_cbranch_scc1 .Lp4e_m1_rg5
	s_cmp_eq_u32 s9, 6
	s_cbranch_scc1 .Lp4e_m1_rg6
	s_cmp_eq_u32 s9, 7
	s_cbranch_scc1 .Lp4e_m1_rg7
.Lp4e_m1_rg0:
	s_add_u32 s100, s28, 0x0
	s_addc_u32 s101, s29, 0
	v_pk_fma_f32 v[142:143], v[142:143], v[164:165], v[54:55] op_sel_hi:[1,0,1]
	v_pk_fma_f32 v[144:145], v[144:145], v[164:165], v[56:57] op_sel_hi:[1,0,1]
	v_pk_fma_f32 v[138:139], v[138:139], v[164:165], v[50:51] op_sel_hi:[1,0,1]
	v_pk_fma_f32 v[140:141], v[140:141], v[164:165], v[52:53] op_sel_hi:[1,0,1]
	v_pk_fma_f32 v[134:135], v[134:135], v[164:165], v[46:47] op_sel_hi:[1,0,1]
	v_pk_fma_f32 v[136:137], v[136:137], v[164:165], v[48:49] op_sel_hi:[1,0,1]
	v_pk_fma_f32 v[130:131], v[130:131], v[164:165], v[42:43] op_sel_hi:[1,0,1]
	v_pk_fma_f32 v[132:133], v[132:133], v[164:165], v[44:45] op_sel_hi:[1,0,1]
	v_pk_mul_f32 v[230:231], v[142:143], v[134:135]
	v_pk_mul_f32 v[232:233], v[144:145], v[136:137]
	v_pk_mul_f32 v[234:235], v[138:139], v[130:131]
	v_pk_mul_f32 v[236:237], v[140:141], v[132:133]
	v_cvt_pk_bf16_f32 v172, v230, v231
	v_cvt_pk_bf16_f32 v173, v232, v233
	v_cvt_pk_bf16_f32 v174, v234, v235
	v_cvt_pk_bf16_f32 v175, v236, v237
	global_store_dwordx4 v176, v[172:175], s[100:101]
	s_add_i32 s8, s8, -1
	s_cmp_eq_u32 s8, 0
	s_cbranch_scc1 .Lp4e_end
.Lp4e_m1_rg1:
	s_add_u32 s100, s28, 0x8000
	s_addc_u32 s101, s29, 0
	v_pk_fma_f32 v[126:127], v[126:127], v[166:167], v[54:55] op_sel_hi:[1,0,1]
	v_pk_fma_f32 v[128:129], v[128:129], v[166:167], v[56:57] op_sel_hi:[1,0,1]
	v_pk_fma_f32 v[122:123], v[122:123], v[166:167], v[50:51] op_sel_hi:[1,0,1]
	v_pk_fma_f32 v[124:125], v[124:125], v[166:167], v[52:53] op_sel_hi:[1,0,1]
	v_pk_fma_f32 v[118:119], v[118:119], v[166:167], v[46:47] op_sel_hi:[1,0,1]
	v_pk_fma_f32 v[120:121], v[120:121], v[166:167], v[48:49] op_sel_hi:[1,0,1]
	v_pk_fma_f32 v[114:115], v[114:115], v[166:167], v[42:43] op_sel_hi:[1,0,1]
	v_pk_fma_f32 v[116:117], v[116:117], v[166:167], v[44:45] op_sel_hi:[1,0,1]
	v_pk_mul_f32 v[230:231], v[126:127], v[118:119]
	v_pk_mul_f32 v[232:233], v[128:129], v[120:121]
	v_pk_mul_f32 v[234:235], v[122:123], v[114:115]
	v_pk_mul_f32 v[236:237], v[124:125], v[116:117]
	v_cvt_pk_bf16_f32 v196, v230, v231
	v_cvt_pk_bf16_f32 v197, v232, v233
	v_cvt_pk_bf16_f32 v198, v234, v235
	v_cvt_pk_bf16_f32 v199, v236, v237
	global_store_dwordx4 v176, v[196:199], s[100:101]
	s_add_i32 s8, s8, -1
	s_cmp_eq_u32 s8, 0
	s_cbranch_scc1 .Lp4e_end
; __device__ __forceinline__ u32x4 pack8(const f32x4 a, const f32x4 b) { u32x4 w; w.x = cvt_pk_bf16(a[0], a[1]); w.y = cvt_pk_bf16(a[2], a[3]); w.z = cvt_pk_bf16(b[0], b[1]); w.w = cvt_pk_bf16(b[2], b[3]); return w; }
;     __device__ __forceinline__ void operator()(const f32x4 (&acc)[2][2][4][2], const Unit& u, int wr, int wc, int fr, int fq) const {
;     ...
;         for (int r = 0; r < 8; ++r) { const int ai = r >> 2, m = r & 3; const int row = EPI_ROW; const float rs = rsv[ai][m];
;             f32x4 a0 = acc[ai][0][m][0] * rs + ba0, a1 = acc[ai][0][m][1] * rs + ba1, b0 = acc[ai][1][m][0] * rs + bb0, b1 = acc[ai][1][m][1] * rs + bb1;
;             bf16_t* rp = dst + (size_t)row * pitch;
;             if (mode == 1) { *(u32x4*)(rp + c0) = pack8(a0 * b0, a1 * b1); }
.Lp4e_m1_rg2:
	s_add_u32 s100, s28, 0x10000
	s_addc_u32 s101, s29, 0
	v_pk_fma_f32 v[110:111], v[110:111], v[168:169], v[54:55] op_sel_hi:[1,0,1]
	v_pk_fma_f32 v[112:113], v[112:113], v[168:169], v[56:57] op_sel_hi:[1,0,1]
	v_pk_fma_f32 v[106:107], v[106:107], v[168:169], v[50:51] op_sel_hi:[1,0,1]
	v_pk_fma_f32 v[108:109], v[108:109], v[168:169], v[52:53] op_sel_hi:[1,0,1]
	v_pk_fma_f32 v[102:103], v[102:103], v[168:169], v[46:47] op_sel_hi:[1,0,1]
	v_pk_fma_f32 v[104:105], v[104:105], v[168:169], v[48:49] op_sel_hi:[1,0,1]
	v_pk_fma_f32 v[98:99], v[98:99], v[168:169], v[42:43] op_sel_hi:[1,0,1]
	v_pk_fma_f32 v[100:101], v[100:101], v[168:169], v[44:45] op_sel_hi:[1,0,1]
	v_pk_mul_f32 v[230:231], v[110:111], v[102:103]
	v_pk_mul_f32 v[232:233], v[112:113], v[104:105]
	v_pk_mul_f32 v[234:235], v[106:107], v[98:99]
	v_pk_mul_f32 v[236:237], v[108:109], v[100:101]
	v_cvt_pk_bf16_f32 v172, v230, v231
	v_cvt_pk_bf16_f32 v173, v232, v233
	v_cvt_pk_bf16_f32 v174, v234, v235
	v_cvt_pk_bf16_f32 v175, v236, v237
	global_store_dwordx4 v176, v[172:175], s[100:101]
	s_add_i32 s8, s8, -1
	s_cmp_eq_u32 s8, 0
	s_cbranch_scc1 .Lp4e_end
.Lp4e_m1_rg3:
	s_add_u32 s100, s28, 0x18000
	s_addc_u32 s101, s29, 0
	v_pk_fma_f32 v[94:95], v[94:95], v[170:171], v[54:55] op_sel_hi:[1,0,1]
	v_pk_fma_f32 v[96:97], v[96:97], v[170:171], v[56:57] op_sel_hi:[1,0,1]
	v_pk_fma_f32 v[90:91], v[90:91], v[170:171], v[50:51] op_sel_hi:[1,0,1]
	v_pk_fma_f32 v[92:93], v[92:93], v[170:171], v[52:53] op_sel_hi:[1,0,1]
	v_pk_fma_f32 v[86:87], v[86:87], v[170:171], v[46:47] op_sel_hi:[1,0,1]
	v_pk_fma_f32 v[88:89], v[88:89], v[170:171], v[48:49] op_sel_hi:[1,0,1]
	v_pk_fma_f32 v[82:83], v[82:83], v[170:171], v[42:43] op_sel_hi:[1,0,1]
	v_pk_fma_f32 v[84:85], v[84:85], v[170:171], v[44:45] op_sel_hi:[1,0,1]
	v_pk_mul_f32 v[230:231], v[94:95], v[86:87]
	v_pk_mul_f32 v[232:233], v[96:97], v[88:89]
	v_pk_mul_f32 v[234:235], v[90:91], v[82:83]
	v_pk_mul_f32 v[236:237], v[92:93], v[84:85]
	v_cvt_pk_bf16_f32 v196, v230, v231
	v_cvt_pk_bf16_f32 v197, v232, v233
	v_cvt_pk_bf16_f32 v198, v234, v235
	v_cvt_pk_bf16_f32 v199, v236, v237
	global_store_dwordx4 v176, v[196:199], s[100:101]
	s_add_i32 s8, s8, -1
	s_cmp_eq_u32 s8, 0
	s_cbranch_scc1 .Lp4e_end
.Lp4e_m1_rg4:
	s_add_u32 s100, s28, 0x40000
	s_addc_u32 s101, s29, 0
	v_pk_fma_f32 v[78:79], v[78:79], v[156:157], v[54:55] op_sel_hi:[1,0,1]
	v_pk_fma_f32 v[80:81], v[80:81], v[156:157], v[56:57] op_sel_hi:[1,0,1]
	v_pk_fma_f32 v[74:75], v[74:75], v[156:157], v[50:51] op_sel_hi:[1,0,1]
	v_pk_fma_f32 v[76:77], v[76:77], v[156:157], v[52:53] op_sel_hi:[1,0,1]
	v_pk_fma_f32 v[70:71], v[70:71], v[156:157], v[46:47] op_sel_hi:[1,0,1]
	v_pk_fma_f32 v[72:73], v[72:73], v[156:157], v[48:49] op_sel_hi:[1,0,1]
	v_pk_fma_f32 v[66:67], v[66:67], v[156:157], v[42:43] op_sel_hi:[1,0,1]
	v_pk_fma_f32 v[68:69], v[68:69], v[156:157], v[44:45] op_sel_hi:[1,0,1]
	v_pk_mul_f32 v[230:231], v[78:79], v[70:71]
	v_pk_mul_f32 v[232:233], v[80:81], v[72:73]
	v_pk_mul_f32 v[234:235], v[74:75], v[66:67]
	v_pk_mul_f32 v[236:237], v[76:77], v[68:69]
	v_cvt_pk_bf16_f32 v172, v230, v231
	v_cvt_pk_bf16_f32 v173, v232, v233
	v_cvt_pk_bf16_f32 v174, v234, v235
	v_cvt_pk_bf16_f32 v175, v236, v237
	global_store_dwordx4 v176, v[172:175], s[100:101]
	s_add_i32 s8, s8, -1
	s_cmp_eq_u32 s8, 0
	s_cbranch_scc1 .Lp4e_end
.Lp4e_m1_rg5:
	s_add_u32 s100, s28, 0x48000
	s_addc_u32 s101, s29, 0
	v_pk_fma_f32 v[62:63], v[62:63], v[158:159], v[54:55] op_sel_hi:[1,0,1]
	v_pk_fma_f32 v[64:65], v[64:65], v[158:159], v[56:57] op_sel_hi:[1,0,1]
	v_pk_fma_f32 v[58:59], v[58:59], v[158:159], v[50:51] op_sel_hi:[1,0,1]
	v_pk_fma_f32 v[60:61], v[60:61], v[158:159], v[52:53] op_sel_hi:[1,0,1]
	v_pk_fma_f32 v[38:39], v[38:39], v[158:159], v[46:47] op_sel_hi:[1,0,1]
	v_pk_fma_f32 v[40:41], v[40:41], v[158:159], v[48:49] op_sel_hi:[1,0,1]
	v_pk_fma_f32 v[34:35], v[34:35], v[158:159], v[42:43] op_sel_hi:[1,0,1]
	v_pk_fma_f32 v[36:37], v[36:37], v[158:159], v[44:45] op_sel_hi:[1,0,1]
	v_pk_mul_f32 v[230:231], v[62:63], v[38:39]
	v_pk_mul_f32 v[232:233], v[64:65], v[40:41]
	v_pk_mul_f32 v[234:235], v[58:59], v[34:35]
	v_pk_mul_f32 v[236:237], v[60:61], v[36:37]
	v_cvt_pk_bf16_f32 v196, v230, v231
	v_cvt_pk_bf16_f32 v197, v232, v233
	v_cvt_pk_bf16_f32 v198, v234, v235
	v_cvt_pk_bf16_f32 v199, v236, v237
	global_store_dwordx4 v176, v[196:199], s[100:101]
	s_add_i32 s8, s8, -1
	s_cmp_eq_u32 s8, 0
	s_cbranch_scc1 .Lp4e_end
.Lp4e_m1_rg6:
	s_add_u32 s100, s28, 0x50000
	s_addc_u32 s101, s29, 0
	v_pk_fma_f32 v[30:31], v[30:31], v[160:161], v[54:55] op_sel_hi:[1,0,1]
	v_pk_fma_f32 v[32:33], v[32:33], v[160:161], v[56:57] op_sel_hi:[1,0,1]
	v_pk_fma_f32 v[26:27], v[26:27], v[160:161], v[50:51] op_sel_hi:[1,0,1]
	v_pk_fma_f32 v[28:29], v[28:29], v[160:161], v[52:53] op_sel_hi:[1,0,1]
	v_pk_fma_f32 v[22:23], v[22:23], v[160:161], v[46:47] op_sel_hi:[1,0,1]
	v_pk_fma_f32 v[24:25], v[24:25], v[160:161], v[48:49] op_sel_hi:[1,0,1]
	v_pk_fma_f32 v[18:19], v[18:19], v[160:161], v[42:43] op_sel_hi:[1,0,1]
	v_pk_fma_f32 v[20:21], v[20:21], v[160:161], v[44:45] op_sel_hi:[1,0,1]
	v_pk_mul_f32 v[230:231], v[30:31], v[22:23]
	v_pk_mul_f32 v[232:233], v[32:33], v[24:25]
	v_pk_mul_f32 v[234:235], v[26:27], v[18:19]
	v_pk_mul_f32 v[236:237], v[28:29], v[20:21]
	v_cvt_pk_bf16_f32 v172, v230, v231
	v_cvt_pk_bf16_f32 v173, v232, v233
	v_cvt_pk_bf16_f32 v174, v234, v235
	v_cvt_pk_bf16_f32 v175, v236, v237
	global_store_dwordx4 v176, v[172:175], s[100:101]
	s_add_i32 s8, s8, -1
	s_cmp_eq_u32 s8, 0
	s_cbranch_scc1 .Lp4e_end
; __device__ __forceinline__ u32x4 pack8(const f32x4 a, const f32x4 b) { u32x4 w; w.x = cvt_pk_bf16(a[0], a[1]); w.y = cvt_pk_bf16(a[2], a[3]); w.z = cvt_pk_bf16(b[0], b[1]); w.w = cvt_pk_bf16(b[2], b[3]); return w; }
;     __device__ __forceinline__ void operator()(const f32x4 (&acc)[2][2][4][2], const Unit& u, int wr, int wc, int fr, int fq) const {
;     ...
;         for (int r = 0; r < 8; ++r) { const int ai = r >> 2, m = r & 3; const int row = EPI_ROW; const float rs = rsv[ai][m];
;             f32x4 a0 = acc[ai][0][m][0] * rs + ba0, a1 = acc[ai][0][m][1] * rs + ba1, b0 = acc[ai][1][m][0] * rs + bb0, b1 = acc[ai][1][m][1] * rs + bb1;
;             bf16_t* rp = dst + (size_t)row * pitch;
;             if (mode == 1) { *(u32x4*)(rp + c0) = pack8(a0 * b0, a1 * b1); }
;             else if (mode == 3) {
; #pragma unroll
;                 for (int i = 0; i < 4; ++i) {
;                     const float ea0 = __expf(-a0[i]), ea1 = __expf(-a1[i]), eb0 = __expf(-b0[i]), eb1 = __expf(-b1[i]);
;                     a0[i] = (1.f + eb0) * __builtin_amdgcn_rcpf(1.f + ea0); a1[i] = (1.f + eb1) * __builtin_amdgcn_rcpf(1.f + ea1); b0[i] = __builtin_amdgcn_rcpf(1.f + eb0); b1[i] = __builtin_amdgcn_rcpf(1.f + eb1); }
;                 { const size_t po = (size_t)(row >> 1) * (2 * DM) + ((pn - 18) * 4 + wc) * 64 + (row & 1) * 32 + fq * 8;
;                   *(u32x4*)(SZC + po) = pack8(a0, a1); *(u32x4*)(SZA + po) = pack8(b0, b1); } }
.Lp4e_m1_rg7:
	s_add_u32 s100, s28, 0x58000
	s_addc_u32 s101, s29, 0
	v_pk_fma_f32 v[14:15], v[14:15], v[162:163], v[54:55] op_sel_hi:[1,0,1]
	v_pk_fma_f32 v[16:17], v[16:17], v[162:163], v[56:57] op_sel_hi:[1,0,1]
	v_pk_fma_f32 v[10:11], v[10:11], v[162:163], v[50:51] op_sel_hi:[1,0,1]
	v_pk_fma_f32 v[12:13], v[12:13], v[162:163], v[52:53] op_sel_hi:[1,0,1]
	v_pk_fma_f32 v[6:7], v[6:7], v[162:163], v[46:47] op_sel_hi:[1,0,1]
	v_pk_fma_f32 v[8:9], v[8:9], v[162:163], v[48:49] op_sel_hi:[1,0,1]
	v_pk_fma_f32 v[2:3], v[2:3], v[162:163], v[42:43] op_sel_hi:[1,0,1]
	v_pk_fma_f32 v[4:5], v[4:5], v[162:163], v[44:45] op_sel_hi:[1,0,1]
	v_pk_mul_f32 v[230:231], v[14:15], v[6:7]
	v_pk_mul_f32 v[232:233], v[16:17], v[8:9]
	v_pk_mul_f32 v[234:235], v[10:11], v[2:3]
	v_pk_mul_f32 v[236:237], v[12:13], v[4:5]
	v_cvt_pk_bf16_f32 v196, v230, v231
	v_cvt_pk_bf16_f32 v197, v232, v233
	v_cvt_pk_bf16_f32 v198, v234, v235
	v_cvt_pk_bf16_f32 v199, v236, v237
	global_store_dwordx4 v176, v[196:199], s[100:101]
	s_add_i32 s8, s8, -1
	s_cmp_eq_u32 s8, 0
	s_cbranch_scc1 .Lp4e_end
	s_branch .Lp4e_m1_rg0
.Lp4e_m3:
	v_mov_b32_e32 v202, 0x358637bd
	v_lshlrev_b32_e32 v146, 6, v1
	v_lshl_add_u32 v147, v201, 10, v146
	v_add_u32_e32 v147, s89, v147
	ds_read_b128 v[148:151], v147
	ds_read_b128 v[152:155], v147 offset:16
	ds_read_b128 v[156:159], v147 offset:32
	ds_read_b128 v[160:163], v147 offset:48
	ds_read_b128 v[230:233], v147 offset:8192
	ds_read_b128 v[234:237], v147 offset:8208
	ds_read_b128 v[238:241], v147 offset:8224
	ds_read_b128 v[242:245], v147 offset:8240
	s_lshl_b32 s5, s4, 8
	s_add_i32 s5, s5, s79
	s_lshl_b32 s5, s5, 11
	s_add_i32 s7, s6, -18
	s_lshl_b32 s7, s7, 9
	s_lshl_b32 s9, s83, 1
	s_add_i32 s7, s7, s9
	s_add_u32 s5, s5, s7
	s_add_u32 s28, s34, s5
	s_addc_u32 s29, s35, 0
	s_add_u32 s52, s36, s5
	s_addc_u32 s53, s37, 0
	v_lshrrev_b32_e32 v176, 1, v1
	v_lshlrev_b32_e32 v176, 12, v176
	v_and_b32_e32 v204, 1, v1
	v_lshl_add_u32 v176, v204, 6, v176
	v_lshl_add_u32 v176, v201, 4, v176
	s_lshr_b32 s9, s79, 4
	s_lshr_b32 s8, s80, 5
	s_add_u32 s9, s9, s8
	s_mov_b32 s8, 8
	s_waitcnt lgkmcnt(4)
	v_pk_add_f32 v[150:151], v[150:151], v[154:155]
	v_pk_add_f32 v[148:149], v[148:149], v[152:153]
	v_pk_add_f32 v[152:153], v[158:159], v[162:163]
	v_pk_add_f32 v[154:155], v[156:157], v[160:161]
	v_pk_add_f32 v[150:151], v[150:151], v[152:153]
	v_pk_add_f32 v[148:149], v[148:149], v[154:155]
	v_add_f32_e32 v148, v148, v149
	v_add_f32_e32 v150, v150, v151
	v_add_f32_e32 v148, v148, v150
	v_fmamk_f32 v148, v148, 0x3a800000, v202
	v_rsq_f32_e32 v148, v148
	s_waitcnt lgkmcnt(0)
	v_pk_add_f32 v[232:233], v[232:233], v[236:237]
	v_pk_add_f32 v[230:231], v[230:231], v[234:235]
	v_pk_add_f32 v[234:235], v[240:241], v[244:245]
	v_pk_add_f32 v[236:237], v[238:239], v[242:243]
	v_pk_add_f32 v[232:233], v[232:233], v[234:235]
	v_pk_add_f32 v[230:231], v[230:231], v[236:237]
	v_add_f32_e32 v230, v230, v231
	v_add_f32_e32 v232, v232, v233
	v_add_f32_e32 v230, v230, v232
	v_fmamk_f32 v230, v230, 0x3a800000, v202
	v_rsq_f32_e32 v230, v230
	v_lshlrev_b32_e32 v149, 2, v1
	v_add_u32_e32 v150, 0x40, v149
	v_add_u32_e32 v151, 0x80, v149
	v_add_u32_e32 v153, 0xc0, v149
	ds_bpermute_b32 v164, v149, v148
	ds_bpermute_b32 v166, v150, v148
	ds_bpermute_b32 v168, v151, v148
	ds_bpermute_b32 v170, v153, v148
	ds_bpermute_b32 v156, v149, v230
	ds_bpermute_b32 v158, v150, v230
	ds_bpermute_b32 v160, v151, v230
	ds_bpermute_b32 v162, v153, v230
	v_mov_b32_e32 v204, 0xbfb8aa3b
	v_mov_b32_e32 v205, 0xbfb8aa3b
	s_waitcnt lgkmcnt(0)
	s_cmp_eq_u32 s9, 1
	s_cbranch_scc1 .Lp4e_m3_rg1
	s_cmp_eq_u32 s9, 2
	s_cbranch_scc1 .Lp4e_m3_rg2
	s_cmp_eq_u32 s9, 3
	s_cbranch_scc1 .Lp4e_m3_rg3
	s_cmp_eq_u32 s9, 4
	s_cbranch_scc1 .Lp4e_m3_rg4
	s_cmp_eq_u32 s9, 5
	s_cbranch_scc1 .Lp4e_m3_rg5
	s_cmp_eq_u32 s9, 6
	s_cbranch_scc1 .Lp4e_m3_rg6
	s_cmp_eq_u32 s9, 7
	s_cbranch_scc1 .Lp4e_m3_rg7
.Lp4e_m3_rg0:
	s_add_u32 s100, s28, 0x0
	s_addc_u32 s101, s29, 0
	s_add_u32 s98, s52, 0x0
	s_addc_u32 s99, s53, 0
	v_pk_fma_f32 v[142:143], v[142:143], v[164:165], v[54:55] op_sel_hi:[1,0,1]
	v_pk_fma_f32 v[144:145], v[144:145], v[164:165], v[56:57] op_sel_hi:[1,0,1]
	v_pk_fma_f32 v[138:139], v[138:139], v[164:165], v[50:51] op_sel_hi:[1,0,1]
	v_pk_fma_f32 v[140:141], v[140:141], v[164:165], v[52:53] op_sel_hi:[1,0,1]
	v_pk_fma_f32 v[134:135], v[134:135], v[164:165], v[46:47] op_sel_hi:[1,0,1]
	v_pk_fma_f32 v[136:137], v[136:137], v[164:165], v[48:49] op_sel_hi:[1,0,1]
	v_pk_fma_f32 v[130:131], v[130:131], v[164:165], v[42:43] op_sel_hi:[1,0,1]
	v_pk_fma_f32 v[132:133], v[132:133], v[164:165], v[44:45] op_sel_hi:[1,0,1]
	v_pk_mul_f32 v[230:231], v[204:205], v[142:143]
	v_pk_mul_f32 v[232:233], v[204:205], v[144:145]
	v_pk_mul_f32 v[234:235], v[204:205], v[138:139]
	v_pk_mul_f32 v[236:237], v[204:205], v[140:141]
	v_pk_mul_f32 v[238:239], v[204:205], v[134:135]
	v_pk_mul_f32 v[240:241], v[204:205], v[136:137]
	v_pk_mul_f32 v[242:243], v[204:205], v[130:131]
	v_pk_mul_f32 v[244:245], v[204:205], v[132:133]
	v_exp_f32_e32 v230, v230
	v_exp_f32_e32 v231, v231
	v_exp_f32_e32 v232, v232
	v_exp_f32_e32 v233, v233
	v_exp_f32_e32 v234, v234
	v_exp_f32_e32 v235, v235
	v_exp_f32_e32 v236, v236
	v_exp_f32_e32 v237, v237
	v_exp_f32_e32 v238, v238
	v_exp_f32_e32 v239, v239
	v_exp_f32_e32 v240, v240
	v_exp_f32_e32 v241, v241
	v_exp_f32_e32 v242, v242
	v_exp_f32_e32 v243, v243
	v_exp_f32_e32 v244, v244
	v_exp_f32_e32 v245, v245
	v_pk_add_f32 v[230:231], v[230:231], 1.0 op_sel_hi:[1,0]
	v_pk_add_f32 v[232:233], v[232:233], 1.0 op_sel_hi:[1,0]
	v_pk_add_f32 v[234:235], v[234:235], 1.0 op_sel_hi:[1,0]
	v_pk_add_f32 v[236:237], v[236:237], 1.0 op_sel_hi:[1,0]
	v_pk_add_f32 v[238:239], v[238:239], 1.0 op_sel_hi:[1,0]
	v_pk_add_f32 v[240:241], v[240:241], 1.0 op_sel_hi:[1,0]
	v_pk_add_f32 v[242:243], v[242:243], 1.0 op_sel_hi:[1,0]
	v_pk_add_f32 v[244:245], v[244:245], 1.0 op_sel_hi:[1,0]
	v_rcp_f32_e32 v212, v230
	v_rcp_f32_e32 v213, v231
	v_rcp_f32_e32 v214, v232
	v_rcp_f32_e32 v215, v233
	v_rcp_f32_e32 v216, v234
	v_rcp_f32_e32 v217, v235
	v_rcp_f32_e32 v218, v236
	v_rcp_f32_e32 v219, v237
	v_rcp_f32_e32 v222, v238
	v_rcp_f32_e32 v223, v239
	v_rcp_f32_e32 v224, v240
	v_rcp_f32_e32 v225, v241
	v_rcp_f32_e32 v226, v242
	v_rcp_f32_e32 v227, v243
	v_rcp_f32_e32 v246, v244
	v_rcp_f32_e32 v247, v245
	v_pk_mul_f32 v[230:231], v[238:239], v[212:213]
	v_pk_mul_f32 v[232:233], v[240:241], v[214:215]
	v_pk_mul_f32 v[234:235], v[242:243], v[216:217]
	v_pk_mul_f32 v[236:237], v[244:245], v[218:219]
	v_cvt_pk_bf16_f32 v172, v230, v231
	v_cvt_pk_bf16_f32 v173, v232, v233
	v_cvt_pk_bf16_f32 v174, v234, v235
	v_cvt_pk_bf16_f32 v175, v236, v237
	global_store_dwordx4 v176, v[172:175], s[100:101]
	v_cvt_pk_bf16_f32 v196, v222, v223
	v_cvt_pk_bf16_f32 v197, v224, v225
	v_cvt_pk_bf16_f32 v198, v226, v227
	v_cvt_pk_bf16_f32 v199, v246, v247
	global_store_dwordx4 v176, v[196:199], s[98:99]
	s_add_i32 s8, s8, -1
	s_cmp_eq_u32 s8, 0
	s_cbranch_scc1 .Lp4e_end
; __device__ __forceinline__ u32x4 pack8(const f32x4 a, const f32x4 b) { u32x4 w; w.x = cvt_pk_bf16(a[0], a[1]); w.y = cvt_pk_bf16(a[2], a[3]); w.z = cvt_pk_bf16(b[0], b[1]); w.w = cvt_pk_bf16(b[2], b[3]); return w; }
;     __device__ __forceinline__ void operator()(const f32x4 (&acc)[2][2][4][2], const Unit& u, int wr, int wc, int fr, int fq) const {
;     ...
;                 for (int i = 0; i < 4; ++i) {
;                     const float ea0 = __expf(-a0[i]), ea1 = __expf(-a1[i]), eb0 = __expf(-b0[i]), eb1 = __expf(-b1[i]);
;                     a0[i] = (1.f + eb0) * __builtin_amdgcn_rcpf(1.f + ea0); a1[i] = (1.f + eb1) * __builtin_amdgcn_rcpf(1.f + ea1); b0[i] = __builtin_amdgcn_rcpf(1.f + eb0); b1[i] = __builtin_amdgcn_rcpf(1.f + eb1); }
;                 { const size_t po = (size_t)(row >> 1) * (2 * DM) + ((pn - 18) * 4 + wc) * 64 + (row & 1) * 32 + fq * 8;
;                   *(u32x4*)(SZC + po) = pack8(a0, a1); *(u32x4*)(SZA + po) = pack8(b0, b1); } }
.Lp4e_m3_rg1:
	s_add_u32 s100, s28, 0x8000
	s_addc_u32 s101, s29, 0
	s_add_u32 s98, s52, 0x8000
	s_addc_u32 s99, s53, 0
	v_pk_fma_f32 v[126:127], v[126:127], v[166:167], v[54:55] op_sel_hi:[1,0,1]
	v_pk_fma_f32 v[128:129], v[128:129], v[166:167], v[56:57] op_sel_hi:[1,0,1]
	v_pk_fma_f32 v[122:123], v[122:123], v[166:167], v[50:51] op_sel_hi:[1,0,1]
	v_pk_fma_f32 v[124:125], v[124:125], v[166:167], v[52:53] op_sel_hi:[1,0,1]
	v_pk_fma_f32 v[118:119], v[118:119], v[166:167], v[46:47] op_sel_hi:[1,0,1]
	v_pk_fma_f32 v[120:121], v[120:121], v[166:167], v[48:49] op_sel_hi:[1,0,1]
	v_pk_fma_f32 v[114:115], v[114:115], v[166:167], v[42:43] op_sel_hi:[1,0,1]
	v_pk_fma_f32 v[116:117], v[116:117], v[166:167], v[44:45] op_sel_hi:[1,0,1]
	v_pk_mul_f32 v[230:231], v[204:205], v[126:127]
	v_pk_mul_f32 v[232:233], v[204:205], v[128:129]
	v_pk_mul_f32 v[234:235], v[204:205], v[122:123]
	v_pk_mul_f32 v[236:237], v[204:205], v[124:125]
	v_pk_mul_f32 v[238:239], v[204:205], v[118:119]
	v_pk_mul_f32 v[240:241], v[204:205], v[120:121]
	v_pk_mul_f32 v[242:243], v[204:205], v[114:115]
	v_pk_mul_f32 v[244:245], v[204:205], v[116:117]
	v_exp_f32_e32 v230, v230
	v_exp_f32_e32 v231, v231
	v_exp_f32_e32 v232, v232
	v_exp_f32_e32 v233, v233
	v_exp_f32_e32 v234, v234
	v_exp_f32_e32 v235, v235
	v_exp_f32_e32 v236, v236
	v_exp_f32_e32 v237, v237
	v_exp_f32_e32 v238, v238
	v_exp_f32_e32 v239, v239
	v_exp_f32_e32 v240, v240
	v_exp_f32_e32 v241, v241
	v_exp_f32_e32 v242, v242
	v_exp_f32_e32 v243, v243
	v_exp_f32_e32 v244, v244
	v_exp_f32_e32 v245, v245
	v_pk_add_f32 v[230:231], v[230:231], 1.0 op_sel_hi:[1,0]
	v_pk_add_f32 v[232:233], v[232:233], 1.0 op_sel_hi:[1,0]
	v_pk_add_f32 v[234:235], v[234:235], 1.0 op_sel_hi:[1,0]
	v_pk_add_f32 v[236:237], v[236:237], 1.0 op_sel_hi:[1,0]
	v_pk_add_f32 v[238:239], v[238:239], 1.0 op_sel_hi:[1,0]
	v_pk_add_f32 v[240:241], v[240:241], 1.0 op_sel_hi:[1,0]
	v_pk_add_f32 v[242:243], v[242:243], 1.0 op_sel_hi:[1,0]
	v_pk_add_f32 v[244:245], v[244:245], 1.0 op_sel_hi:[1,0]
	v_rcp_f32_e32 v212, v230
	v_rcp_f32_e32 v213, v231
	v_rcp_f32_e32 v214, v232
	v_rcp_f32_e32 v215, v233
	v_rcp_f32_e32 v216, v234
	v_rcp_f32_e32 v217, v235
	v_rcp_f32_e32 v218, v236
	v_rcp_f32_e32 v219, v237
	v_rcp_f32_e32 v222, v238
	v_rcp_f32_e32 v223, v239
	v_rcp_f32_e32 v224, v240
	v_rcp_f32_e32 v225, v241
	v_rcp_f32_e32 v226, v242
	v_rcp_f32_e32 v227, v243
	v_rcp_f32_e32 v246, v244
	v_rcp_f32_e32 v247, v245
	v_pk_mul_f32 v[230:231], v[238:239], v[212:213]
	v_pk_mul_f32 v[232:233], v[240:241], v[214:215]
	v_pk_mul_f32 v[234:235], v[242:243], v[216:217]
	v_pk_mul_f32 v[236:237], v[244:245], v[218:219]
	v_cvt_pk_bf16_f32 v172, v230, v231
	v_cvt_pk_bf16_f32 v173, v232, v233
	v_cvt_pk_bf16_f32 v174, v234, v235
	v_cvt_pk_bf16_f32 v175, v236, v237
	global_store_dwordx4 v176, v[172:175], s[100:101]
	v_cvt_pk_bf16_f32 v196, v222, v223
	v_cvt_pk_bf16_f32 v197, v224, v225
	v_cvt_pk_bf16_f32 v198, v226, v227
	v_cvt_pk_bf16_f32 v199, v246, v247
	global_store_dwordx4 v176, v[196:199], s[98:99]
	s_add_i32 s8, s8, -1
	s_cmp_eq_u32 s8, 0
	s_cbranch_scc1 .Lp4e_end
.Lp4e_m3_rg2:
	s_add_u32 s100, s28, 0x10000
	s_addc_u32 s101, s29, 0
	s_add_u32 s98, s52, 0x10000
	s_addc_u32 s99, s53, 0
	v_pk_fma_f32 v[110:111], v[110:111], v[168:169], v[54:55] op_sel_hi:[1,0,1]
	v_pk_fma_f32 v[112:113], v[112:113], v[168:169], v[56:57] op_sel_hi:[1,0,1]
	v_pk_fma_f32 v[106:107], v[106:107], v[168:169], v[50:51] op_sel_hi:[1,0,1]
	v_pk_fma_f32 v[108:109], v[108:109], v[168:169], v[52:53] op_sel_hi:[1,0,1]
	v_pk_fma_f32 v[102:103], v[102:103], v[168:169], v[46:47] op_sel_hi:[1,0,1]
	v_pk_fma_f32 v[104:105], v[104:105], v[168:169], v[48:49] op_sel_hi:[1,0,1]
	v_pk_fma_f32 v[98:99], v[98:99], v[168:169], v[42:43] op_sel_hi:[1,0,1]
	v_pk_fma_f32 v[100:101], v[100:101], v[168:169], v[44:45] op_sel_hi:[1,0,1]
	v_pk_mul_f32 v[230:231], v[204:205], v[110:111]
	v_pk_mul_f32 v[232:233], v[204:205], v[112:113]
	v_pk_mul_f32 v[234:235], v[204:205], v[106:107]
	v_pk_mul_f32 v[236:237], v[204:205], v[108:109]
	v_pk_mul_f32 v[238:239], v[204:205], v[102:103]
	v_pk_mul_f32 v[240:241], v[204:205], v[104:105]
	v_pk_mul_f32 v[242:243], v[204:205], v[98:99]
	v_pk_mul_f32 v[244:245], v[204:205], v[100:101]
	v_exp_f32_e32 v230, v230
	v_exp_f32_e32 v231, v231
	v_exp_f32_e32 v232, v232
	v_exp_f32_e32 v233, v233
	v_exp_f32_e32 v234, v234
	v_exp_f32_e32 v235, v235
	v_exp_f32_e32 v236, v236
	v_exp_f32_e32 v237, v237
	v_exp_f32_e32 v238, v238
	v_exp_f32_e32 v239, v239
	v_exp_f32_e32 v240, v240
	v_exp_f32_e32 v241, v241
	v_exp_f32_e32 v242, v242
	v_exp_f32_e32 v243, v243
	v_exp_f32_e32 v244, v244
	v_exp_f32_e32 v245, v245
	v_pk_add_f32 v[230:231], v[230:231], 1.0 op_sel_hi:[1,0]
	v_pk_add_f32 v[232:233], v[232:233], 1.0 op_sel_hi:[1,0]
	v_pk_add_f32 v[234:235], v[234:235], 1.0 op_sel_hi:[1,0]
	v_pk_add_f32 v[236:237], v[236:237], 1.0 op_sel_hi:[1,0]
	v_pk_add_f32 v[238:239], v[238:239], 1.0 op_sel_hi:[1,0]
	v_pk_add_f32 v[240:241], v[240:241], 1.0 op_sel_hi:[1,0]
	v_pk_add_f32 v[242:243], v[242:243], 1.0 op_sel_hi:[1,0]
	v_pk_add_f32 v[244:245], v[244:245], 1.0 op_sel_hi:[1,0]
	v_rcp_f32_e32 v212, v230
	v_rcp_f32_e32 v213, v231
	v_rcp_f32_e32 v214, v232
	v_rcp_f32_e32 v215, v233
	v_rcp_f32_e32 v216, v234
	v_rcp_f32_e32 v217, v235
	v_rcp_f32_e32 v218, v236
	v_rcp_f32_e32 v219, v237
	v_rcp_f32_e32 v222, v238
	v_rcp_f32_e32 v223, v239
	v_rcp_f32_e32 v224, v240
	v_rcp_f32_e32 v225, v241
	v_rcp_f32_e32 v226, v242
	v_rcp_f32_e32 v227, v243
	v_rcp_f32_e32 v246, v244
	v_rcp_f32_e32 v247, v245
	v_pk_mul_f32 v[230:231], v[238:239], v[212:213]
	v_pk_mul_f32 v[232:233], v[240:241], v[214:215]
	v_pk_mul_f32 v[234:235], v[242:243], v[216:217]
	v_pk_mul_f32 v[236:237], v[244:245], v[218:219]
	v_cvt_pk_bf16_f32 v172, v230, v231
	v_cvt_pk_bf16_f32 v173, v232, v233
	v_cvt_pk_bf16_f32 v174, v234, v235
	v_cvt_pk_bf16_f32 v175, v236, v237
	global_store_dwordx4 v176, v[172:175], s[100:101]
	v_cvt_pk_bf16_f32 v196, v222, v223
	v_cvt_pk_bf16_f32 v197, v224, v225
	v_cvt_pk_bf16_f32 v198, v226, v227
	v_cvt_pk_bf16_f32 v199, v246, v247
	global_store_dwordx4 v176, v[196:199], s[98:99]
	s_add_i32 s8, s8, -1
	s_cmp_eq_u32 s8, 0
	s_cbranch_scc1 .Lp4e_end
; __device__ __forceinline__ u32x4 pack8(const f32x4 a, const f32x4 b) { u32x4 w; w.x = cvt_pk_bf16(a[0], a[1]); w.y = cvt_pk_bf16(a[2], a[3]); w.z = cvt_pk_bf16(b[0], b[1]); w.w = cvt_pk_bf16(b[2], b[3]); return w; }
;     __device__ __forceinline__ void operator()(const f32x4 (&acc)[2][2][4][2], const Unit& u, int wr, int wc, int fr, int fq) const {
;     ...
;                 for (int i = 0; i < 4; ++i) {
;                     const float ea0 = __expf(-a0[i]), ea1 = __expf(-a1[i]), eb0 = __expf(-b0[i]), eb1 = __expf(-b1[i]);
;                     a0[i] = (1.f + eb0) * __builtin_amdgcn_rcpf(1.f + ea0); a1[i] = (1.f + eb1) * __builtin_amdgcn_rcpf(1.f + ea1); b0[i] = __builtin_amdgcn_rcpf(1.f + eb0); b1[i] = __builtin_amdgcn_rcpf(1.f + eb1); }
;                 { const size_t po = (size_t)(row >> 1) * (2 * DM) + ((pn - 18) * 4 + wc) * 64 + (row & 1) * 32 + fq * 8;
;                   *(u32x4*)(SZC + po) = pack8(a0, a1); *(u32x4*)(SZA + po) = pack8(b0, b1); } }
.Lp4e_m3_rg3:
	s_add_u32 s100, s28, 0x18000
	s_addc_u32 s101, s29, 0
	s_add_u32 s98, s52, 0x18000
	s_addc_u32 s99, s53, 0
	v_pk_fma_f32 v[94:95], v[94:95], v[170:171], v[54:55] op_sel_hi:[1,0,1]
	v_pk_fma_f32 v[96:97], v[96:97], v[170:171], v[56:57] op_sel_hi:[1,0,1]
	v_pk_fma_f32 v[90:91], v[90:91], v[170:171], v[50:51] op_sel_hi:[1,0,1]
	v_pk_fma_f32 v[92:93], v[92:93], v[170:171], v[52:53] op_sel_hi:[1,0,1]
	v_pk_fma_f32 v[86:87], v[86:87], v[170:171], v[46:47] op_sel_hi:[1,0,1]
	v_pk_fma_f32 v[88:89], v[88:89], v[170:171], v[48:49] op_sel_hi:[1,0,1]
	v_pk_fma_f32 v[82:83], v[82:83], v[170:171], v[42:43] op_sel_hi:[1,0,1]
	v_pk_fma_f32 v[84:85], v[84:85], v[170:171], v[44:45] op_sel_hi:[1,0,1]
	v_pk_mul_f32 v[230:231], v[204:205], v[94:95]
	v_pk_mul_f32 v[232:233], v[204:205], v[96:97]
	v_pk_mul_f32 v[234:235], v[204:205], v[90:91]
	v_pk_mul_f32 v[236:237], v[204:205], v[92:93]
	v_pk_mul_f32 v[238:239], v[204:205], v[86:87]
	v_pk_mul_f32 v[240:241], v[204:205], v[88:89]
	v_pk_mul_f32 v[242:243], v[204:205], v[82:83]
	v_pk_mul_f32 v[244:245], v[204:205], v[84:85]
	v_exp_f32_e32 v230, v230
	v_exp_f32_e32 v231, v231
	v_exp_f32_e32 v232, v232
	v_exp_f32_e32 v233, v233
	v_exp_f32_e32 v234, v234
	v_exp_f32_e32 v235, v235
	v_exp_f32_e32 v236, v236
	v_exp_f32_e32 v237, v237
	v_exp_f32_e32 v238, v238
	v_exp_f32_e32 v239, v239
	v_exp_f32_e32 v240, v240
	v_exp_f32_e32 v241, v241
	v_exp_f32_e32 v242, v242
	v_exp_f32_e32 v243, v243
	v_exp_f32_e32 v244, v244
	v_exp_f32_e32 v245, v245
	v_pk_add_f32 v[230:231], v[230:231], 1.0 op_sel_hi:[1,0]
	v_pk_add_f32 v[232:233], v[232:233], 1.0 op_sel_hi:[1,0]
	v_pk_add_f32 v[234:235], v[234:235], 1.0 op_sel_hi:[1,0]
	v_pk_add_f32 v[236:237], v[236:237], 1.0 op_sel_hi:[1,0]
	v_pk_add_f32 v[238:239], v[238:239], 1.0 op_sel_hi:[1,0]
	v_pk_add_f32 v[240:241], v[240:241], 1.0 op_sel_hi:[1,0]
	v_pk_add_f32 v[242:243], v[242:243], 1.0 op_sel_hi:[1,0]
	v_pk_add_f32 v[244:245], v[244:245], 1.0 op_sel_hi:[1,0]
	v_rcp_f32_e32 v212, v230
	v_rcp_f32_e32 v213, v231
	v_rcp_f32_e32 v214, v232
	v_rcp_f32_e32 v215, v233
	v_rcp_f32_e32 v216, v234
	v_rcp_f32_e32 v217, v235
	v_rcp_f32_e32 v218, v236
	v_rcp_f32_e32 v219, v237
	v_rcp_f32_e32 v222, v238
	v_rcp_f32_e32 v223, v239
	v_rcp_f32_e32 v224, v240
	v_rcp_f32_e32 v225, v241
	v_rcp_f32_e32 v226, v242
	v_rcp_f32_e32 v227, v243
	v_rcp_f32_e32 v246, v244
	v_rcp_f32_e32 v247, v245
	v_pk_mul_f32 v[230:231], v[238:239], v[212:213]
	v_pk_mul_f32 v[232:233], v[240:241], v[214:215]
	v_pk_mul_f32 v[234:235], v[242:243], v[216:217]
	v_pk_mul_f32 v[236:237], v[244:245], v[218:219]
	v_cvt_pk_bf16_f32 v172, v230, v231
	v_cvt_pk_bf16_f32 v173, v232, v233
	v_cvt_pk_bf16_f32 v174, v234, v235
	v_cvt_pk_bf16_f32 v175, v236, v237
	global_store_dwordx4 v176, v[172:175], s[100:101]
	v_cvt_pk_bf16_f32 v196, v222, v223
	v_cvt_pk_bf16_f32 v197, v224, v225
	v_cvt_pk_bf16_f32 v198, v226, v227
	v_cvt_pk_bf16_f32 v199, v246, v247
	global_store_dwordx4 v176, v[196:199], s[98:99]
	s_add_i32 s8, s8, -1
	s_cmp_eq_u32 s8, 0
	s_cbranch_scc1 .Lp4e_end
.Lp4e_m3_rg4:
	s_add_u32 s100, s28, 0x40000
	s_addc_u32 s101, s29, 0
	s_add_u32 s98, s52, 0x40000
	s_addc_u32 s99, s53, 0
	v_pk_fma_f32 v[78:79], v[78:79], v[156:157], v[54:55] op_sel_hi:[1,0,1]
	v_pk_fma_f32 v[80:81], v[80:81], v[156:157], v[56:57] op_sel_hi:[1,0,1]
	v_pk_fma_f32 v[74:75], v[74:75], v[156:157], v[50:51] op_sel_hi:[1,0,1]
	v_pk_fma_f32 v[76:77], v[76:77], v[156:157], v[52:53] op_sel_hi:[1,0,1]
	v_pk_fma_f32 v[70:71], v[70:71], v[156:157], v[46:47] op_sel_hi:[1,0,1]
	v_pk_fma_f32 v[72:73], v[72:73], v[156:157], v[48:49] op_sel_hi:[1,0,1]
	v_pk_fma_f32 v[66:67], v[66:67], v[156:157], v[42:43] op_sel_hi:[1,0,1]
	v_pk_fma_f32 v[68:69], v[68:69], v[156:157], v[44:45] op_sel_hi:[1,0,1]
	v_pk_mul_f32 v[230:231], v[204:205], v[78:79]
	v_pk_mul_f32 v[232:233], v[204:205], v[80:81]
	v_pk_mul_f32 v[234:235], v[204:205], v[74:75]
	v_pk_mul_f32 v[236:237], v[204:205], v[76:77]
	v_pk_mul_f32 v[238:239], v[204:205], v[70:71]
	v_pk_mul_f32 v[240:241], v[204:205], v[72:73]
	v_pk_mul_f32 v[242:243], v[204:205], v[66:67]
	v_pk_mul_f32 v[244:245], v[204:205], v[68:69]
	v_exp_f32_e32 v230, v230
	v_exp_f32_e32 v231, v231
	v_exp_f32_e32 v232, v232
	v_exp_f32_e32 v233, v233
	v_exp_f32_e32 v234, v234
	v_exp_f32_e32 v235, v235
	v_exp_f32_e32 v236, v236
	v_exp_f32_e32 v237, v237
	v_exp_f32_e32 v238, v238
	v_exp_f32_e32 v239, v239
	v_exp_f32_e32 v240, v240
	v_exp_f32_e32 v241, v241
	v_exp_f32_e32 v242, v242
	v_exp_f32_e32 v243, v243
	v_exp_f32_e32 v244, v244
	v_exp_f32_e32 v245, v245
	v_pk_add_f32 v[230:231], v[230:231], 1.0 op_sel_hi:[1,0]
	v_pk_add_f32 v[232:233], v[232:233], 1.0 op_sel_hi:[1,0]
	v_pk_add_f32 v[234:235], v[234:235], 1.0 op_sel_hi:[1,0]
	v_pk_add_f32 v[236:237], v[236:237], 1.0 op_sel_hi:[1,0]
	v_pk_add_f32 v[238:239], v[238:239], 1.0 op_sel_hi:[1,0]
	v_pk_add_f32 v[240:241], v[240:241], 1.0 op_sel_hi:[1,0]
	v_pk_add_f32 v[242:243], v[242:243], 1.0 op_sel_hi:[1,0]
	v_pk_add_f32 v[244:245], v[244:245], 1.0 op_sel_hi:[1,0]
	v_rcp_f32_e32 v212, v230
	v_rcp_f32_e32 v213, v231
	v_rcp_f32_e32 v214, v232
	v_rcp_f32_e32 v215, v233
	v_rcp_f32_e32 v216, v234
	v_rcp_f32_e32 v217, v235
	v_rcp_f32_e32 v218, v236
	v_rcp_f32_e32 v219, v237
	v_rcp_f32_e32 v222, v238
	v_rcp_f32_e32 v223, v239
	v_rcp_f32_e32 v224, v240
	v_rcp_f32_e32 v225, v241
	v_rcp_f32_e32 v226, v242
	v_rcp_f32_e32 v227, v243
	v_rcp_f32_e32 v246, v244
	v_rcp_f32_e32 v247, v245
	v_pk_mul_f32 v[230:231], v[238:239], v[212:213]
	v_pk_mul_f32 v[232:233], v[240:241], v[214:215]
	v_pk_mul_f32 v[234:235], v[242:243], v[216:217]
	v_pk_mul_f32 v[236:237], v[244:245], v[218:219]
	v_cvt_pk_bf16_f32 v172, v230, v231
	v_cvt_pk_bf16_f32 v173, v232, v233
	v_cvt_pk_bf16_f32 v174, v234, v235
	v_cvt_pk_bf16_f32 v175, v236, v237
	global_store_dwordx4 v176, v[172:175], s[100:101]
	v_cvt_pk_bf16_f32 v196, v222, v223
	v_cvt_pk_bf16_f32 v197, v224, v225
	v_cvt_pk_bf16_f32 v198, v226, v227
	v_cvt_pk_bf16_f32 v199, v246, v247
	global_store_dwordx4 v176, v[196:199], s[98:99]
	s_add_i32 s8, s8, -1
	s_cmp_eq_u32 s8, 0
	s_cbranch_scc1 .Lp4e_end
; __device__ __forceinline__ u32x4 pack8(const f32x4 a, const f32x4 b) { u32x4 w; w.x = cvt_pk_bf16(a[0], a[1]); w.y = cvt_pk_bf16(a[2], a[3]); w.z = cvt_pk_bf16(b[0], b[1]); w.w = cvt_pk_bf16(b[2], b[3]); return w; }
;     __device__ __forceinline__ void operator()(const f32x4 (&acc)[2][2][4][2], const Unit& u, int wr, int wc, int fr, int fq) const {
;     ...
;                 for (int i = 0; i < 4; ++i) {
;                     const float ea0 = __expf(-a0[i]), ea1 = __expf(-a1[i]), eb0 = __expf(-b0[i]), eb1 = __expf(-b1[i]);
;                     a0[i] = (1.f + eb0) * __builtin_amdgcn_rcpf(1.f + ea0); a1[i] = (1.f + eb1) * __builtin_amdgcn_rcpf(1.f + ea1); b0[i] = __builtin_amdgcn_rcpf(1.f + eb0); b1[i] = __builtin_amdgcn_rcpf(1.f + eb1); }
;                 { const size_t po = (size_t)(row >> 1) * (2 * DM) + ((pn - 18) * 4 + wc) * 64 + (row & 1) * 32 + fq * 8;
;                   *(u32x4*)(SZC + po) = pack8(a0, a1); *(u32x4*)(SZA + po) = pack8(b0, b1); } }
.Lp4e_m3_rg5:
	s_add_u32 s100, s28, 0x48000
	s_addc_u32 s101, s29, 0
	s_add_u32 s98, s52, 0x48000
	s_addc_u32 s99, s53, 0
	v_pk_fma_f32 v[62:63], v[62:63], v[158:159], v[54:55] op_sel_hi:[1,0,1]
	v_pk_fma_f32 v[64:65], v[64:65], v[158:159], v[56:57] op_sel_hi:[1,0,1]
	v_pk_fma_f32 v[58:59], v[58:59], v[158:159], v[50:51] op_sel_hi:[1,0,1]
	v_pk_fma_f32 v[60:61], v[60:61], v[158:159], v[52:53] op_sel_hi:[1,0,1]
	v_pk_fma_f32 v[38:39], v[38:39], v[158:159], v[46:47] op_sel_hi:[1,0,1]
	v_pk_fma_f32 v[40:41], v[40:41], v[158:159], v[48:49] op_sel_hi:[1,0,1]
	v_pk_fma_f32 v[34:35], v[34:35], v[158:159], v[42:43] op_sel_hi:[1,0,1]
	v_pk_fma_f32 v[36:37], v[36:37], v[158:159], v[44:45] op_sel_hi:[1,0,1]
	v_pk_mul_f32 v[230:231], v[204:205], v[62:63]
	v_pk_mul_f32 v[232:233], v[204:205], v[64:65]
	v_pk_mul_f32 v[234:235], v[204:205], v[58:59]
	v_pk_mul_f32 v[236:237], v[204:205], v[60:61]
	v_pk_mul_f32 v[238:239], v[204:205], v[38:39]
	v_pk_mul_f32 v[240:241], v[204:205], v[40:41]
	v_pk_mul_f32 v[242:243], v[204:205], v[34:35]
	v_pk_mul_f32 v[244:245], v[204:205], v[36:37]
	v_exp_f32_e32 v230, v230
	v_exp_f32_e32 v231, v231
	v_exp_f32_e32 v232, v232
	v_exp_f32_e32 v233, v233
	v_exp_f32_e32 v234, v234
	v_exp_f32_e32 v235, v235
	v_exp_f32_e32 v236, v236
	v_exp_f32_e32 v237, v237
	v_exp_f32_e32 v238, v238
	v_exp_f32_e32 v239, v239
	v_exp_f32_e32 v240, v240
	v_exp_f32_e32 v241, v241
	v_exp_f32_e32 v242, v242
	v_exp_f32_e32 v243, v243
	v_exp_f32_e32 v244, v244
	v_exp_f32_e32 v245, v245
	v_pk_add_f32 v[230:231], v[230:231], 1.0 op_sel_hi:[1,0]
	v_pk_add_f32 v[232:233], v[232:233], 1.0 op_sel_hi:[1,0]
	v_pk_add_f32 v[234:235], v[234:235], 1.0 op_sel_hi:[1,0]
	v_pk_add_f32 v[236:237], v[236:237], 1.0 op_sel_hi:[1,0]
	v_pk_add_f32 v[238:239], v[238:239], 1.0 op_sel_hi:[1,0]
	v_pk_add_f32 v[240:241], v[240:241], 1.0 op_sel_hi:[1,0]
	v_pk_add_f32 v[242:243], v[242:243], 1.0 op_sel_hi:[1,0]
	v_pk_add_f32 v[244:245], v[244:245], 1.0 op_sel_hi:[1,0]
	v_rcp_f32_e32 v212, v230
	v_rcp_f32_e32 v213, v231
	v_rcp_f32_e32 v214, v232
	v_rcp_f32_e32 v215, v233
	v_rcp_f32_e32 v216, v234
	v_rcp_f32_e32 v217, v235
	v_rcp_f32_e32 v218, v236
	v_rcp_f32_e32 v219, v237
	v_rcp_f32_e32 v222, v238
	v_rcp_f32_e32 v223, v239
	v_rcp_f32_e32 v224, v240
	v_rcp_f32_e32 v225, v241
	v_rcp_f32_e32 v226, v242
	v_rcp_f32_e32 v227, v243
	v_rcp_f32_e32 v246, v244
	v_rcp_f32_e32 v247, v245
	v_pk_mul_f32 v[230:231], v[238:239], v[212:213]
	v_pk_mul_f32 v[232:233], v[240:241], v[214:215]
	v_pk_mul_f32 v[234:235], v[242:243], v[216:217]
	v_pk_mul_f32 v[236:237], v[244:245], v[218:219]
	v_cvt_pk_bf16_f32 v172, v230, v231
	v_cvt_pk_bf16_f32 v173, v232, v233
	v_cvt_pk_bf16_f32 v174, v234, v235
	v_cvt_pk_bf16_f32 v175, v236, v237
	global_store_dwordx4 v176, v[172:175], s[100:101]
	v_cvt_pk_bf16_f32 v196, v222, v223
	v_cvt_pk_bf16_f32 v197, v224, v225
	v_cvt_pk_bf16_f32 v198, v226, v227
	v_cvt_pk_bf16_f32 v199, v246, v247
	global_store_dwordx4 v176, v[196:199], s[98:99]
	s_add_i32 s8, s8, -1
	s_cmp_eq_u32 s8, 0
	s_cbranch_scc1 .Lp4e_end
.Lp4e_m3_rg6:
	s_add_u32 s100, s28, 0x50000
	s_addc_u32 s101, s29, 0
	s_add_u32 s98, s52, 0x50000
	s_addc_u32 s99, s53, 0
	v_pk_fma_f32 v[30:31], v[30:31], v[160:161], v[54:55] op_sel_hi:[1,0,1]
	v_pk_fma_f32 v[32:33], v[32:33], v[160:161], v[56:57] op_sel_hi:[1,0,1]
	v_pk_fma_f32 v[26:27], v[26:27], v[160:161], v[50:51] op_sel_hi:[1,0,1]
	v_pk_fma_f32 v[28:29], v[28:29], v[160:161], v[52:53] op_sel_hi:[1,0,1]
	v_pk_fma_f32 v[22:23], v[22:23], v[160:161], v[46:47] op_sel_hi:[1,0,1]
	v_pk_fma_f32 v[24:25], v[24:25], v[160:161], v[48:49] op_sel_hi:[1,0,1]
	v_pk_fma_f32 v[18:19], v[18:19], v[160:161], v[42:43] op_sel_hi:[1,0,1]
	v_pk_fma_f32 v[20:21], v[20:21], v[160:161], v[44:45] op_sel_hi:[1,0,1]
	v_pk_mul_f32 v[230:231], v[204:205], v[30:31]
	v_pk_mul_f32 v[232:233], v[204:205], v[32:33]
	v_pk_mul_f32 v[234:235], v[204:205], v[26:27]
	v_pk_mul_f32 v[236:237], v[204:205], v[28:29]
	v_pk_mul_f32 v[238:239], v[204:205], v[22:23]
	v_pk_mul_f32 v[240:241], v[204:205], v[24:25]
	v_pk_mul_f32 v[242:243], v[204:205], v[18:19]
	v_pk_mul_f32 v[244:245], v[204:205], v[20:21]
	v_exp_f32_e32 v230, v230
	v_exp_f32_e32 v231, v231
	v_exp_f32_e32 v232, v232
	v_exp_f32_e32 v233, v233
	v_exp_f32_e32 v234, v234
	v_exp_f32_e32 v235, v235
	v_exp_f32_e32 v236, v236
	v_exp_f32_e32 v237, v237
	v_exp_f32_e32 v238, v238
	v_exp_f32_e32 v239, v239
	v_exp_f32_e32 v240, v240
	v_exp_f32_e32 v241, v241
	v_exp_f32_e32 v242, v242
	v_exp_f32_e32 v243, v243
	v_exp_f32_e32 v244, v244
	v_exp_f32_e32 v245, v245
	v_pk_add_f32 v[230:231], v[230:231], 1.0 op_sel_hi:[1,0]
	v_pk_add_f32 v[232:233], v[232:233], 1.0 op_sel_hi:[1,0]
	v_pk_add_f32 v[234:235], v[234:235], 1.0 op_sel_hi:[1,0]
	v_pk_add_f32 v[236:237], v[236:237], 1.0 op_sel_hi:[1,0]
	v_pk_add_f32 v[238:239], v[238:239], 1.0 op_sel_hi:[1,0]
	v_pk_add_f32 v[240:241], v[240:241], 1.0 op_sel_hi:[1,0]
	v_pk_add_f32 v[242:243], v[242:243], 1.0 op_sel_hi:[1,0]
	v_pk_add_f32 v[244:245], v[244:245], 1.0 op_sel_hi:[1,0]
	v_rcp_f32_e32 v212, v230
	v_rcp_f32_e32 v213, v231
	v_rcp_f32_e32 v214, v232
	v_rcp_f32_e32 v215, v233
	v_rcp_f32_e32 v216, v234
	v_rcp_f32_e32 v217, v235
	v_rcp_f32_e32 v218, v236
	v_rcp_f32_e32 v219, v237
	v_rcp_f32_e32 v222, v238
	v_rcp_f32_e32 v223, v239
	v_rcp_f32_e32 v224, v240
	v_rcp_f32_e32 v225, v241
	v_rcp_f32_e32 v226, v242
	v_rcp_f32_e32 v227, v243
	v_rcp_f32_e32 v246, v244
	v_rcp_f32_e32 v247, v245
	v_pk_mul_f32 v[230:231], v[238:239], v[212:213]
	v_pk_mul_f32 v[232:233], v[240:241], v[214:215]
	v_pk_mul_f32 v[234:235], v[242:243], v[216:217]
	v_pk_mul_f32 v[236:237], v[244:245], v[218:219]
	v_cvt_pk_bf16_f32 v172, v230, v231
	v_cvt_pk_bf16_f32 v173, v232, v233
	v_cvt_pk_bf16_f32 v174, v234, v235
	v_cvt_pk_bf16_f32 v175, v236, v237
	global_store_dwordx4 v176, v[172:175], s[100:101]
	v_cvt_pk_bf16_f32 v196, v222, v223
	v_cvt_pk_bf16_f32 v197, v224, v225
	v_cvt_pk_bf16_f32 v198, v226, v227
	v_cvt_pk_bf16_f32 v199, v246, v247
	global_store_dwordx4 v176, v[196:199], s[98:99]
	s_add_i32 s8, s8, -1
	s_cmp_eq_u32 s8, 0
	s_cbranch_scc1 .Lp4e_end
; __device__ __forceinline__ u32x4 pack8(const f32x4 a, const f32x4 b) { u32x4 w; w.x = cvt_pk_bf16(a[0], a[1]); w.y = cvt_pk_bf16(a[2], a[3]); w.z = cvt_pk_bf16(b[0], b[1]); w.w = cvt_pk_bf16(b[2], b[3]); return w; }
;     __device__ __forceinline__ void operator()(const f32x4 (&acc)[2][2][4][2], const Unit& u, int wr, int wc, int fr, int fq) const {
;     ...
;                 for (int i = 0; i < 4; ++i) {
;                     const float ea0 = __expf(-a0[i]), ea1 = __expf(-a1[i]), eb0 = __expf(-b0[i]), eb1 = __expf(-b1[i]);
;                     a0[i] = (1.f + eb0) * __builtin_amdgcn_rcpf(1.f + ea0); a1[i] = (1.f + eb1) * __builtin_amdgcn_rcpf(1.f + ea1); b0[i] = __builtin_amdgcn_rcpf(1.f + eb0); b1[i] = __builtin_amdgcn_rcpf(1.f + eb1); }
;                 { const size_t po = (size_t)(row >> 1) * (2 * DM) + ((pn - 18) * 4 + wc) * 64 + (row & 1) * 32 + fq * 8;
;                   *(u32x4*)(SZC + po) = pack8(a0, a1); *(u32x4*)(SZA + po) = pack8(b0, b1); } }
.Lp4e_m3_rg7:
	s_add_u32 s100, s28, 0x58000
	s_addc_u32 s101, s29, 0
	s_add_u32 s98, s52, 0x58000
	s_addc_u32 s99, s53, 0
	v_pk_fma_f32 v[14:15], v[14:15], v[162:163], v[54:55] op_sel_hi:[1,0,1]
	v_pk_fma_f32 v[16:17], v[16:17], v[162:163], v[56:57] op_sel_hi:[1,0,1]
	v_pk_fma_f32 v[10:11], v[10:11], v[162:163], v[50:51] op_sel_hi:[1,0,1]
	v_pk_fma_f32 v[12:13], v[12:13], v[162:163], v[52:53] op_sel_hi:[1,0,1]
	v_pk_fma_f32 v[6:7], v[6:7], v[162:163], v[46:47] op_sel_hi:[1,0,1]
	v_pk_fma_f32 v[8:9], v[8:9], v[162:163], v[48:49] op_sel_hi:[1,0,1]
	v_pk_fma_f32 v[2:3], v[2:3], v[162:163], v[42:43] op_sel_hi:[1,0,1]
	v_pk_fma_f32 v[4:5], v[4:5], v[162:163], v[44:45] op_sel_hi:[1,0,1]
	v_pk_mul_f32 v[230:231], v[204:205], v[14:15]
	v_pk_mul_f32 v[232:233], v[204:205], v[16:17]
	v_pk_mul_f32 v[234:235], v[204:205], v[10:11]
	v_pk_mul_f32 v[236:237], v[204:205], v[12:13]
	v_pk_mul_f32 v[238:239], v[204:205], v[6:7]
	v_pk_mul_f32 v[240:241], v[204:205], v[8:9]
	v_pk_mul_f32 v[242:243], v[204:205], v[2:3]
	v_pk_mul_f32 v[244:245], v[204:205], v[4:5]
	v_exp_f32_e32 v230, v230
	v_exp_f32_e32 v231, v231
	v_exp_f32_e32 v232, v232
	v_exp_f32_e32 v233, v233
	v_exp_f32_e32 v234, v234
	v_exp_f32_e32 v235, v235
	v_exp_f32_e32 v236, v236
	v_exp_f32_e32 v237, v237
	v_exp_f32_e32 v238, v238
	v_exp_f32_e32 v239, v239
	v_exp_f32_e32 v240, v240
	v_exp_f32_e32 v241, v241
	v_exp_f32_e32 v242, v242
	v_exp_f32_e32 v243, v243
	v_exp_f32_e32 v244, v244
	v_exp_f32_e32 v245, v245
	v_pk_add_f32 v[230:231], v[230:231], 1.0 op_sel_hi:[1,0]
	v_pk_add_f32 v[232:233], v[232:233], 1.0 op_sel_hi:[1,0]
	v_pk_add_f32 v[234:235], v[234:235], 1.0 op_sel_hi:[1,0]
	v_pk_add_f32 v[236:237], v[236:237], 1.0 op_sel_hi:[1,0]
	v_pk_add_f32 v[238:239], v[238:239], 1.0 op_sel_hi:[1,0]
	v_pk_add_f32 v[240:241], v[240:241], 1.0 op_sel_hi:[1,0]
	v_pk_add_f32 v[242:243], v[242:243], 1.0 op_sel_hi:[1,0]
	v_pk_add_f32 v[244:245], v[244:245], 1.0 op_sel_hi:[1,0]
	v_rcp_f32_e32 v212, v230
	v_rcp_f32_e32 v213, v231
	v_rcp_f32_e32 v214, v232
	v_rcp_f32_e32 v215, v233
	v_rcp_f32_e32 v216, v234
	v_rcp_f32_e32 v217, v235
	v_rcp_f32_e32 v218, v236
	v_rcp_f32_e32 v219, v237
	v_rcp_f32_e32 v222, v238
	v_rcp_f32_e32 v223, v239
	v_rcp_f32_e32 v224, v240
	v_rcp_f32_e32 v225, v241
	v_rcp_f32_e32 v226, v242
	v_rcp_f32_e32 v227, v243
	v_rcp_f32_e32 v246, v244
	v_rcp_f32_e32 v247, v245
	v_pk_mul_f32 v[230:231], v[238:239], v[212:213]
	v_pk_mul_f32 v[232:233], v[240:241], v[214:215]
	v_pk_mul_f32 v[234:235], v[242:243], v[216:217]
	v_pk_mul_f32 v[236:237], v[244:245], v[218:219]
	v_cvt_pk_bf16_f32 v172, v230, v231
	v_cvt_pk_bf16_f32 v173, v232, v233
	v_cvt_pk_bf16_f32 v174, v234, v235
	v_cvt_pk_bf16_f32 v175, v236, v237
	global_store_dwordx4 v176, v[172:175], s[100:101]
	v_cvt_pk_bf16_f32 v196, v222, v223
	v_cvt_pk_bf16_f32 v197, v224, v225
	v_cvt_pk_bf16_f32 v198, v226, v227
	v_cvt_pk_bf16_f32 v199, v246, v247
	global_store_dwordx4 v176, v[196:199], s[98:99]
	s_add_i32 s8, s8, -1
	s_cmp_eq_u32 s8, 0
	s_cbranch_scc1 .Lp4e_end
	s_branch .Lp4e_m3_rg0
.Lp4e_end:
	s_andn2_b64 vcc, exec, s[2:3]
	s_mov_b64 s[2:3], -1
	s_cbranch_vccnz .LBB0_434
.LBB0_575:
	s_andn2_b64 vcc, exec, s[16:17]
	s_cbranch_vccnz .LBB0_433
	s_barrier
	s_branch .LBB0_433
